# GEMM3 epilogue on sample row panels: all first-touch state_ffn_conv lines prefetched together before the first unrolled iteration; plus no-setprio K-loops, P0 split order, nt loads
# baseline (speedup 1.0000x reference)
; __device__ __forceinline__ float dpp_shr1(float old, float src) { return __builtin_bit_cast(float, __builtin_amdgcn_update_dpp(__builtin_bit_cast(int, old), __builtin_bit_cast(int, src), 0x111, 0xf, 0xf, false)); }
; __device__ __forceinline__ float dpp_shr2(float old, float src) { return __builtin_bit_cast(float, __builtin_amdgcn_update_dpp(__builtin_bit_cast(int, old), __builtin_bit_cast(int, src), 0x112, 0xf, 0xf, false)); }
; __device__ __forceinline__ float dpp_ror1(float src) { return __builtin_bit_cast(float, __builtin_amdgcn_update_dpp(0, __builtin_bit_cast(int, src), 0x121, 0xf, 0xf, false)); }
; __device__ __forceinline__ float dpp_ror2(float src) { return __builtin_bit_cast(float, __builtin_amdgcn_update_dpp(0, __builtin_bit_cast(int, src), 0x122, 0xf, 0xf, false)); }
;     __device__ __forceinline__ void operator()(const f32x4 (&acc)[2][2][4][2], const Unit& u, int wr, int wc, int fr, int fq) const {
;     ...
;                     const int r = u.pm * BM + ai * HALF + wr * 64 + m * 16 + fr;
;                     const float rsm = RS[16 * m]; const f32x4 g = acc[ai][0][m][n] * rsm, uu = acc[ai][1][m][n] * rsm; f32x4 p1, p2, av;
;                     if (!sample) {
; #pragma unroll
;                         for (int e = 0; e < 4; ++e) { float o1, o2;
;                             if (m == 0) { o1 = bm1[e]; o2 = (fr == 0) ? bm2[e] : bm1[e]; } else { const float gp = acc[ai][0][m > 0 ? m - 1 : 0][n][e] * RS[16 * (m > 0 ? m - 1 : 0)]; o1 = dpp_ror1(gp); o2 = dpp_ror2(gp); }
;                             p1[e] = dpp_shr1(o1, g[e]); p2[e] = dpp_shr2(o2, g[e]); }
;                         if (ai == 0 && wr == 0 && m == 0 && fr < 2 && (u.pm & 7) != 0) {
;                             *(f32x4*)(fix + ((size_t)(72 + u.pm * 2 + fr)) * DFF + j0 + 4 * n) = g; *(f32x4*)(fix + ((size_t)(144 + u.pm * 2 + fr)) * DFF + j0 + 4 * n) = uu; }
;                     } else {
;                         const int t = fr & 7, bs = (r - MP) >> 3; f32x4 s0 = (f32x4){0.f, 0.f, 0.f, 0.f}, s1 = s0;
;                         if (t < 2) { s0 = *(const f32x4*)(st_ffn + ((size_t)bs * 2 + 0) * DFF + j0 + 4 * n); s1 = *(const f32x4*)(st_ffn + ((size_t)bs * 2 + 1) * DFF + j0 + 4 * n); }
.LBB0_747:
	s_or_b64 exec, exec, s[6:7]
	v_lshl_add_u32 v187, v186, 2, s28
	ds_read_b32 v188, v187
	v_and_b32_e32 v150, 7, v186
	v_add_u32_e32 v217, s97, v186
	v_cmp_gt_u32_e64 s[14:15], 2, v150
	v_ashrrev_i32_e32 v185, 31, v184
	v_cmp_eq_u32_e64 s[10:11], 0, v150
	v_cmp_lt_u32_e64 s[6:7], 1, v150
	v_cmp_eq_u32_e64 s[8:9], 1, v150
	v_cmp_lt_u32_e64 s[12:13], 5, v150
	v_add_u32_e32 v178, -6, v150
	v_cmp_eq_u32_e64 s[18:19], 0, v186
	v_cmp_lt_i32_e64 s[20:21], 1, v186
	s_waitcnt lgkmcnt(0)
	v_pk_mul_f32 v[152:153], v[148:149], v[188:189] op_sel_hi:[1,0]
	v_pk_mul_f32 v[150:151], v[146:147], v[188:189] op_sel_hi:[1,0]
	s_and_b64 vcc, exec, s[22:23]
	s_cbranch_vccz .LBB0_753
	s_add_i32 s16, s74, 0xffffe000
	v_add_u32_e32 v162, s16, v217
	v_ashrrev_i32_e32 v192, 3, v162
	v_mov_b32_e32 v162, 0
	v_mov_b32_e32 v163, 0
	v_mov_b32_e32 v164, 0
	v_mov_b32_e32 v165, 0
	v_mov_b32_e32 v166, 0
	v_mov_b32_e32 v167, 0
	v_mov_b32_e32 v168, 0
	v_mov_b32_e32 v169, 0
	s_and_saveexec_b64 s[16:17], s[14:15]
	s_cbranch_execz .LBB0_750
	v_mov_b64_e32 v[162:163], s[36:37]
	v_mad_i64_i32 v[162:163], s[82:83], v192, s53, v[162:163]
	v_lshl_add_u64 v[162:163], v[184:185], 2, v[162:163]
	v_add_co_u32_e32 v166, vcc, 0xa000, v162
	s_nop 1
	v_addc_co_u32_e32 v167, vcc, 0, v163, vcc
	s_mov_b64 s[98:99], 0x2b000
	v_lshl_add_u64 v[246:247], v[162:163], 0, s[98:99]
	global_load_dword v248, v[246:247], off
	s_mov_b64 s[98:99], 0x35c00
	v_lshl_add_u64 v[246:247], v[162:163], 0, s[98:99]
	global_load_dword v248, v[246:247], off
	s_mov_b64 s[98:99], 0x56000
	v_lshl_add_u64 v[246:247], v[162:163], 0, s[98:99]
	global_load_dword v248, v[246:247], off
	s_mov_b64 s[98:99], 0x60c00
	v_lshl_add_u64 v[246:247], v[162:163], 0, s[98:99]
	global_load_dword v248, v[246:247], off
	s_mov_b64 s[98:99], 0x81000
	v_lshl_add_u64 v[246:247], v[162:163], 0, s[98:99]
	global_load_dword v248, v[246:247], off
	s_mov_b64 s[98:99], 0x8bc00
	v_lshl_add_u64 v[246:247], v[162:163], 0, s[98:99]
	global_load_dword v248, v[246:247], off
	s_mov_b64 s[98:99], 0x158000
	v_lshl_add_u64 v[246:247], v[162:163], 0, s[98:99]
	global_load_dword v248, v[246:247], off
	s_mov_b64 s[98:99], 0x162c00
	v_lshl_add_u64 v[246:247], v[162:163], 0, s[98:99]
	global_load_dword v248, v[246:247], off
	s_mov_b64 s[98:99], 0x183000
	v_lshl_add_u64 v[246:247], v[162:163], 0, s[98:99]
	global_load_dword v248, v[246:247], off
	s_mov_b64 s[98:99], 0x18dc00
	v_lshl_add_u64 v[246:247], v[162:163], 0, s[98:99]
	global_load_dword v248, v[246:247], off
	s_mov_b64 s[98:99], 0x1ae000
	v_lshl_add_u64 v[246:247], v[162:163], 0, s[98:99]
	global_load_dword v248, v[246:247], off
	s_mov_b64 s[98:99], 0x1b8c00
	v_lshl_add_u64 v[246:247], v[162:163], 0, s[98:99]
	global_load_dword v248, v[246:247], off
	s_mov_b64 s[98:99], 0x1d9000
	v_lshl_add_u64 v[246:247], v[162:163], 0, s[98:99]
	global_load_dword v248, v[246:247], off
	s_mov_b64 s[98:99], 0x1e3c00
	v_lshl_add_u64 v[246:247], v[162:163], 0, s[98:99]
	global_load_dword v248, v[246:247], off
	global_load_dwordx4 v[162:165], v[162:163], off
	s_nop 0
	global_load_dwordx4 v[166:169], v[166:167], off offset:3072
